# G1/G4 epilogues: per-row rstd from ONE linear 1 KiB partial-sum load per 16-row group + quad DPP sum + ds_bpermute to the MFMA row layout (was 4 lane-scattered loads and a vmcnt(0) drain per group)
# speedup vs baseline: 1.0478x; 1.0051x over previous
.LBB0_400:
	s_lshl_b32 s13, s8, 8
	s_add_i32 s13, s13, s46
	v_or_b32_e32 v154, s13, v141
	v_and_b32_e32 v234, -16, v154
	v_lshlrev_b32_e32 v234, 6, v234
	v_lshl_add_u32 v234, v186, 4, v234
	v_add_u32_e32 v235, 0x2000, v234
	global_load_dwordx4 v[202:205], v234, s[0:1]
	global_load_dwordx4 v[206:209], v234, s[0:1] offset:1024
	global_load_dwordx4 v[210:213], v234, s[0:1] offset:2048
	global_load_dwordx4 v[214:217], v234, s[0:1] offset:3072
	global_load_dwordx4 v[218:221], v235, s[0:1]
	global_load_dwordx4 v[222:225], v235, s[0:1] offset:1024
	global_load_dwordx4 v[226:229], v235, s[0:1] offset:2048
	global_load_dwordx4 v[230:233], v235, s[0:1] offset:3072
	v_and_b32_e32 v236, 15, v186
	v_lshlrev_b32_e32 v236, 4, v236
	s_waitcnt vmcnt(0)
	v_add_f32_e32 v202, v202, v203
	v_add_f32_e32 v204, v204, v205
	v_add_f32_e32 v206, v206, v207
	v_add_f32_e32 v208, v208, v209
	v_add_f32_e32 v210, v210, v211
	v_add_f32_e32 v212, v212, v213
	v_add_f32_e32 v214, v214, v215
	v_add_f32_e32 v216, v216, v217
	v_add_f32_e32 v218, v218, v219
	v_add_f32_e32 v220, v220, v221
	v_add_f32_e32 v222, v222, v223
	v_add_f32_e32 v224, v224, v225
	v_add_f32_e32 v226, v226, v227
	v_add_f32_e32 v228, v228, v229
	v_add_f32_e32 v230, v230, v231
	v_add_f32_e32 v232, v232, v233
	v_add_f32_e32 v202, v202, v204
	v_add_f32_e32 v206, v206, v208
	v_add_f32_e32 v210, v210, v212
	v_add_f32_e32 v214, v214, v216
	v_add_f32_e32 v218, v218, v220
	v_add_f32_e32 v222, v222, v224
	v_add_f32_e32 v226, v226, v228
	v_add_f32_e32 v230, v230, v232
	v_add_f32_dpp v202, v202, v202 quad_perm:[1,0,3,2] row_mask:0xf bank_mask:0xf
	v_add_f32_dpp v206, v206, v206 quad_perm:[1,0,3,2] row_mask:0xf bank_mask:0xf
	v_add_f32_dpp v210, v210, v210 quad_perm:[1,0,3,2] row_mask:0xf bank_mask:0xf
	v_add_f32_dpp v214, v214, v214 quad_perm:[1,0,3,2] row_mask:0xf bank_mask:0xf
	v_add_f32_dpp v218, v218, v218 quad_perm:[1,0,3,2] row_mask:0xf bank_mask:0xf
	v_add_f32_dpp v222, v222, v222 quad_perm:[1,0,3,2] row_mask:0xf bank_mask:0xf
	v_add_f32_dpp v226, v226, v226 quad_perm:[1,0,3,2] row_mask:0xf bank_mask:0xf
	v_add_f32_dpp v230, v230, v230 quad_perm:[1,0,3,2] row_mask:0xf bank_mask:0xf
	v_add_f32_dpp v202, v202, v202 quad_perm:[2,3,0,1] row_mask:0xf bank_mask:0xf
	v_add_f32_dpp v206, v206, v206 quad_perm:[2,3,0,1] row_mask:0xf bank_mask:0xf
	v_add_f32_dpp v210, v210, v210 quad_perm:[2,3,0,1] row_mask:0xf bank_mask:0xf
	v_add_f32_dpp v214, v214, v214 quad_perm:[2,3,0,1] row_mask:0xf bank_mask:0xf
	v_add_f32_dpp v218, v218, v218 quad_perm:[2,3,0,1] row_mask:0xf bank_mask:0xf
	v_add_f32_dpp v222, v222, v222 quad_perm:[2,3,0,1] row_mask:0xf bank_mask:0xf
	v_add_f32_dpp v226, v226, v226 quad_perm:[2,3,0,1] row_mask:0xf bank_mask:0xf
	v_add_f32_dpp v230, v230, v230 quad_perm:[2,3,0,1] row_mask:0xf bank_mask:0xf
	v_fmamk_f32 v202, v202, 0x3a800000, v182
	v_fmamk_f32 v206, v206, 0x3a800000, v182
	v_fmamk_f32 v210, v210, 0x3a800000, v182
	v_fmamk_f32 v214, v214, 0x3a800000, v182
	v_fmamk_f32 v218, v218, 0x3a800000, v182
	v_fmamk_f32 v222, v222, 0x3a800000, v182
	v_fmamk_f32 v226, v226, 0x3a800000, v182
	v_fmamk_f32 v230, v230, 0x3a800000, v182
	v_mul_f32_e32 v203, 0x4b800000, v202
	v_mul_f32_e32 v207, 0x4b800000, v206
	v_mul_f32_e32 v211, 0x4b800000, v210
	v_mul_f32_e32 v215, 0x4b800000, v214
	v_mul_f32_e32 v219, 0x4b800000, v218
	v_mul_f32_e32 v223, 0x4b800000, v222
	v_mul_f32_e32 v227, 0x4b800000, v226
	v_mul_f32_e32 v231, 0x4b800000, v230
	v_cmp_gt_f32_e32 vcc, 0x800000, v202
	s_nop 1
	v_cndmask_b32_e32 v204, v202, v203, vcc
	v_rsq_f32_e32 v204, v204
	s_nop 0
	v_mul_f32_e32 v205, 0x45800000, v204
	v_cndmask_b32_e32 v204, v204, v205, vcc
	v_cmp_gt_f32_e32 vcc, 0x800000, v206
	s_nop 1
	v_cndmask_b32_e32 v208, v206, v207, vcc
	v_rsq_f32_e32 v208, v208
	s_nop 0
	v_mul_f32_e32 v209, 0x45800000, v208
	v_cndmask_b32_e32 v208, v208, v209, vcc
	v_cmp_gt_f32_e32 vcc, 0x800000, v210
	s_nop 1
	v_cndmask_b32_e32 v212, v210, v211, vcc
	v_rsq_f32_e32 v212, v212
	s_nop 0
	v_mul_f32_e32 v213, 0x45800000, v212
	v_cndmask_b32_e32 v212, v212, v213, vcc
	v_cmp_gt_f32_e32 vcc, 0x800000, v214
	s_nop 1
	v_cndmask_b32_e32 v216, v214, v215, vcc
	v_rsq_f32_e32 v216, v216
	s_nop 0
	v_mul_f32_e32 v217, 0x45800000, v216
	v_cndmask_b32_e32 v216, v216, v217, vcc
	v_cmp_gt_f32_e32 vcc, 0x800000, v218
	s_nop 1
	v_cndmask_b32_e32 v220, v218, v219, vcc
	v_rsq_f32_e32 v220, v220
	s_nop 0
	v_mul_f32_e32 v221, 0x45800000, v220
	v_cndmask_b32_e32 v220, v220, v221, vcc
	v_cmp_gt_f32_e32 vcc, 0x800000, v222
	s_nop 1
	v_cndmask_b32_e32 v224, v222, v223, vcc
	v_rsq_f32_e32 v224, v224
	s_nop 0
	v_mul_f32_e32 v225, 0x45800000, v224
	v_cndmask_b32_e32 v224, v224, v225, vcc
	v_cmp_gt_f32_e32 vcc, 0x800000, v226
	s_nop 1
	v_cndmask_b32_e32 v228, v226, v227, vcc
	v_rsq_f32_e32 v228, v228
	s_nop 0
	v_mul_f32_e32 v229, 0x45800000, v228
	v_cndmask_b32_e32 v228, v228, v229, vcc
	v_cmp_gt_f32_e32 vcc, 0x800000, v230
	s_nop 1
	v_cndmask_b32_e32 v232, v230, v231, vcc
	v_rsq_f32_e32 v232, v232
	s_nop 0
	v_mul_f32_e32 v233, 0x45800000, v232
	v_cndmask_b32_e32 v232, v232, v233, vcc
	s_nop 1
	ds_bpermute_b32 v238, v236, v204
	ds_bpermute_b32 v239, v236, v208
	ds_bpermute_b32 v240, v236, v212
	ds_bpermute_b32 v241, v236, v216
	ds_bpermute_b32 v242, v236, v220
	ds_bpermute_b32 v243, v236, v224
	ds_bpermute_b32 v244, v236, v228
	ds_bpermute_b32 v245, v236, v232
	s_waitcnt lgkmcnt(0)
	v_ashrrev_i32_e32 v155, 31, v154
	v_lshlrev_b64 v[152:153], 6, v[154:155]
	v_lshl_add_u64 v[152:153], s[0:1], 0, v[152:153]
	s_lshl_b32 s24, s12, 8
	v_or_b32_e32 v155, s13, v145
	s_movk_i32 s8, 0x1320
	v_or_b32_e32 v152, s24, v138
	v_cmp_gt_i32_e64 s[8:9], s8, v152
	v_mov_b32_e32 v156, v238
	v_mov_b32_e32 v157, v156
	s_and_saveexec_b64 s[10:11], s[8:9]
	s_cbranch_execz .LBB0_405
	v_mov_b32_e32 v166, v156
	v_mov_b32_e32 v167, v156
	v_pk_mul_f32 v[128:129], v[128:129], v[166:167]
	v_pk_mul_f32 v[126:127], v[126:127], v[156:157]
	v_pk_mul_f32 v[166:167], v[124:125], v[166:167]
	v_pk_mul_f32 v[124:125], v[122:123], v[156:157]
	s_and_b32 s17, s12, 0xfffffe
	v_cvt_pk_bf16_f32 v122, v126, v127
	v_cvt_pk_bf16_f32 v123, v128, v129
	v_cvt_pk_bf16_f32 v124, v124, v125
	v_cvt_pk_bf16_f32 v125, v166, v167
	s_cmp_lg_u32 s17, 4
	s_mov_b64 s[26:27], -1
	s_cbranch_scc0 .LBB0_403
	v_mov_b64_e32 v[126:127], s[4:5]
	v_mad_i64_i32 v[126:127], s[26:27], v154, s90, v[126:127]
	v_ashrrev_i32_e32 v153, 31, v152
	v_lshl_add_u64 v[126:127], v[152:153], 1, v[126:127]
	global_store_dwordx4 v[126:127], v[122:125], off
	s_mov_b64 s[26:27], 0

.LBB0_415:
	s_or_b64 exec, exec, s[26:27]
	v_or_b32_e32 v114, s13, v147
	v_ashrrev_i32_e32 v115, 31, v114
	v_lshlrev_b64 v[116:117], 6, v[114:115]
	v_lshl_add_u64 v[120:121], s[0:1], 0, v[116:117]
	v_mov_b32_e32 v116, v239
	v_mov_b32_e32 v117, v116
	s_and_saveexec_b64 s[26:27], s[8:9]
	s_cbranch_execz .LBB0_420
	v_mov_b32_e32 v118, v116
	v_mov_b32_e32 v119, v116
	v_pk_mul_f32 v[112:113], v[112:113], v[118:119]
	v_pk_mul_f32 v[110:111], v[110:111], v[116:117]
	v_pk_mul_f32 v[118:119], v[108:109], v[118:119]
	v_pk_mul_f32 v[108:109], v[106:107], v[116:117]
	s_and_b32 s19, s12, 0xfffffe
	v_cvt_pk_bf16_f32 v106, v110, v111
	v_cvt_pk_bf16_f32 v107, v112, v113
	v_cvt_pk_bf16_f32 v108, v108, v109
	v_cvt_pk_bf16_f32 v109, v118, v119
	s_cmp_eq_u32 s19, 4
	s_mov_b64 s[28:29], -1
	s_cbranch_scc1 .LBB0_418
	v_mov_b64_e32 v[110:111], s[4:5]
	v_mad_i64_i32 v[110:111], s[28:29], v114, s90, v[110:111]
	v_ashrrev_i32_e32 v153, 31, v152
	v_lshl_add_u64 v[110:111], v[152:153], 1, v[110:111]
	s_mov_b64 s[28:29], 0
	global_store_dwordx4 v[110:111], v[106:109], off

.LBB0_430:
	s_or_b64 exec, exec, s[26:27]
	v_or_b32_e32 v98, s13, v158
	v_ashrrev_i32_e32 v99, 31, v98
	v_lshlrev_b64 v[100:101], 6, v[98:99]
	v_lshl_add_u64 v[112:113], s[0:1], 0, v[100:101]
	v_mov_b32_e32 v100, v240
	v_mov_b32_e32 v101, v100
	s_and_saveexec_b64 s[26:27], s[8:9]
	s_cbranch_execz .LBB0_435
	v_mov_b32_e32 v102, v100
	v_mov_b32_e32 v103, v100
	v_pk_mul_f32 v[96:97], v[96:97], v[102:103]
	v_pk_mul_f32 v[94:95], v[94:95], v[100:101]
	v_pk_mul_f32 v[102:103], v[92:93], v[102:103]
	v_pk_mul_f32 v[92:93], v[90:91], v[100:101]
	s_and_b32 s19, s12, 0xfffffe
	v_cvt_pk_bf16_f32 v90, v94, v95
	v_cvt_pk_bf16_f32 v91, v96, v97
	v_cvt_pk_bf16_f32 v92, v92, v93
	v_cvt_pk_bf16_f32 v93, v102, v103
	s_cmp_eq_u32 s19, 4
	s_mov_b64 s[28:29], -1
	s_cbranch_scc1 .LBB0_433
	v_mov_b64_e32 v[94:95], s[4:5]
	v_mad_i64_i32 v[94:95], s[28:29], v98, s90, v[94:95]
	v_ashrrev_i32_e32 v153, 31, v152
	v_lshl_add_u64 v[94:95], v[152:153], 1, v[94:95]
	s_mov_b64 s[28:29], 0
	global_store_dwordx4 v[94:95], v[90:93], off

.LBB0_445:
	s_or_b64 exec, exec, s[26:27]
	v_or_b32_e32 v82, s13, v159
	v_ashrrev_i32_e32 v83, 31, v82
	v_lshlrev_b64 v[84:85], 6, v[82:83]
	v_lshl_add_u64 v[96:97], s[0:1], 0, v[84:85]
	v_mov_b32_e32 v84, v241
	v_mov_b32_e32 v85, v84
	s_and_saveexec_b64 s[26:27], s[8:9]
	s_cbranch_execz .LBB0_450
	v_mov_b32_e32 v86, v84
	v_mov_b32_e32 v87, v84
	v_pk_mul_f32 v[80:81], v[80:81], v[86:87]
	v_pk_mul_f32 v[78:79], v[78:79], v[84:85]
	v_pk_mul_f32 v[86:87], v[76:77], v[86:87]
	v_pk_mul_f32 v[76:77], v[74:75], v[84:85]
	s_and_b32 s19, s12, 0xfffffe
	v_cvt_pk_bf16_f32 v74, v78, v79
	v_cvt_pk_bf16_f32 v75, v80, v81
	v_cvt_pk_bf16_f32 v76, v76, v77
	v_cvt_pk_bf16_f32 v77, v86, v87
	s_cmp_eq_u32 s19, 4
	s_mov_b64 s[28:29], -1
	s_cbranch_scc1 .LBB0_448
	v_mov_b64_e32 v[78:79], s[4:5]
	v_mad_i64_i32 v[78:79], s[28:29], v82, s90, v[78:79]
	v_ashrrev_i32_e32 v153, 31, v152
	v_lshl_add_u64 v[78:79], v[152:153], 1, v[78:79]
	s_mov_b64 s[28:29], 0
	global_store_dwordx4 v[78:79], v[74:77], off

.LBB0_460:
	s_or_b64 exec, exec, s[26:27]
	s_addk_i32 s13, 0x80
	v_or_b32_e32 v66, s13, v141
	v_ashrrev_i32_e32 v67, 31, v66
	v_lshlrev_b64 v[68:69], 6, v[66:67]
	v_lshl_add_u64 v[80:81], s[0:1], 0, v[68:69]
	v_mov_b32_e32 v68, v242
	v_mov_b32_e32 v69, v68
	v_or_b32_e32 v67, s13, v145
	s_and_saveexec_b64 s[26:27], s[8:9]
	s_cbranch_execz .LBB0_465
	v_mov_b32_e32 v70, v68
	v_mov_b32_e32 v71, v68
	v_pk_mul_f32 v[64:65], v[64:65], v[70:71]
	v_pk_mul_f32 v[62:63], v[62:63], v[68:69]
	v_pk_mul_f32 v[70:71], v[60:61], v[70:71]
	v_pk_mul_f32 v[60:61], v[58:59], v[68:69]
	s_and_b32 s19, s12, 0xfffffe
	v_cvt_pk_bf16_f32 v58, v62, v63
	v_cvt_pk_bf16_f32 v59, v64, v65
	v_cvt_pk_bf16_f32 v60, v60, v61
	v_cvt_pk_bf16_f32 v61, v70, v71
	s_cmp_eq_u32 s19, 4
	s_mov_b64 s[28:29], -1
	s_cbranch_scc1 .LBB0_463
	v_mov_b64_e32 v[62:63], s[4:5]
	v_mad_i64_i32 v[62:63], s[28:29], v66, s90, v[62:63]
	v_ashrrev_i32_e32 v153, 31, v152
	v_lshl_add_u64 v[62:63], v[152:153], 1, v[62:63]
	s_mov_b64 s[28:29], 0
	global_store_dwordx4 v[62:63], v[58:61], off

.LBB0_475:
	s_or_b64 exec, exec, s[26:27]
	v_or_b32_e32 v50, s13, v147
	v_ashrrev_i32_e32 v51, 31, v50
	v_lshlrev_b64 v[52:53], 6, v[50:51]
	v_lshl_add_u64 v[64:65], s[0:1], 0, v[52:53]
	v_mov_b32_e32 v52, v243
	v_mov_b32_e32 v53, v52
	s_and_saveexec_b64 s[26:27], s[8:9]
	s_cbranch_execz .LBB0_480
	v_mov_b32_e32 v54, v52
	v_mov_b32_e32 v55, v52
	v_pk_mul_f32 v[48:49], v[48:49], v[54:55]
	v_pk_mul_f32 v[46:47], v[46:47], v[52:53]
	v_pk_mul_f32 v[54:55], v[44:45], v[54:55]
	v_pk_mul_f32 v[44:45], v[42:43], v[52:53]
	s_and_b32 s19, s12, 0xfffffe
	v_cvt_pk_bf16_f32 v42, v46, v47
	v_cvt_pk_bf16_f32 v43, v48, v49
	v_cvt_pk_bf16_f32 v44, v44, v45
	v_cvt_pk_bf16_f32 v45, v54, v55
	s_cmp_eq_u32 s19, 4
	s_mov_b64 s[28:29], -1
	s_cbranch_scc1 .LBB0_478
	v_mov_b64_e32 v[46:47], s[4:5]
	v_mad_i64_i32 v[46:47], s[28:29], v50, s90, v[46:47]
	v_ashrrev_i32_e32 v153, 31, v152
	v_lshl_add_u64 v[46:47], v[152:153], 1, v[46:47]
	s_mov_b64 s[28:29], 0
	global_store_dwordx4 v[46:47], v[42:45], off

.LBB0_490:
	s_or_b64 exec, exec, s[26:27]
	v_or_b32_e32 v34, s13, v158
	v_ashrrev_i32_e32 v35, 31, v34
	v_lshlrev_b64 v[36:37], 6, v[34:35]
	v_lshl_add_u64 v[48:49], s[0:1], 0, v[36:37]
	v_mov_b32_e32 v36, v244
	v_mov_b32_e32 v37, v36
	s_and_saveexec_b64 s[26:27], s[8:9]
	s_cbranch_execz .LBB0_495
	v_mov_b32_e32 v38, v36
	v_mov_b32_e32 v39, v36
	v_pk_mul_f32 v[32:33], v[32:33], v[38:39]
	v_pk_mul_f32 v[30:31], v[30:31], v[36:37]
	v_pk_mul_f32 v[38:39], v[28:29], v[38:39]
	v_pk_mul_f32 v[28:29], v[26:27], v[36:37]
	s_and_b32 s19, s12, 0xfffffe
	v_cvt_pk_bf16_f32 v26, v30, v31
	v_cvt_pk_bf16_f32 v27, v32, v33
	v_cvt_pk_bf16_f32 v28, v28, v29
	v_cvt_pk_bf16_f32 v29, v38, v39
	s_cmp_eq_u32 s19, 4
	s_mov_b64 s[28:29], -1
	s_cbranch_scc1 .LBB0_493
	v_mov_b64_e32 v[30:31], s[4:5]
	v_mad_i64_i32 v[30:31], s[28:29], v34, s90, v[30:31]
	v_ashrrev_i32_e32 v153, 31, v152
	v_lshl_add_u64 v[30:31], v[152:153], 1, v[30:31]
	s_mov_b64 s[28:29], 0
	global_store_dwordx4 v[30:31], v[26:29], off

.LBB0_505:
	s_or_b64 exec, exec, s[26:27]
	v_or_b32_e32 v18, s13, v159
	v_ashrrev_i32_e32 v19, 31, v18
	v_lshlrev_b64 v[20:21], 6, v[18:19]
	v_lshl_add_u64 v[32:33], s[0:1], 0, v[20:21]
	v_mov_b32_e32 v20, v245
	v_mov_b32_e32 v21, v20
	s_and_saveexec_b64 s[26:27], s[8:9]
	s_cbranch_execz .LBB0_510
	v_mov_b32_e32 v22, v20
	v_mov_b32_e32 v23, v20
	v_pk_mul_f32 v[16:17], v[16:17], v[22:23]
	v_pk_mul_f32 v[14:15], v[14:15], v[20:21]
	v_pk_mul_f32 v[22:23], v[12:13], v[22:23]
	v_pk_mul_f32 v[12:13], v[10:11], v[20:21]
	s_and_b32 s8, s12, 0xfffffe
	v_cvt_pk_bf16_f32 v10, v14, v15
	v_cvt_pk_bf16_f32 v11, v16, v17
	v_cvt_pk_bf16_f32 v12, v12, v13
	v_cvt_pk_bf16_f32 v13, v22, v23
	s_cmp_eq_u32 s8, 4
	s_mov_b64 s[8:9], -1
	s_cbranch_scc1 .LBB0_508
	v_mov_b64_e32 v[14:15], s[4:5]
	v_mad_i64_i32 v[14:15], s[8:9], v18, s90, v[14:15]
	v_ashrrev_i32_e32 v153, 31, v152
	v_lshl_add_u64 v[14:15], v[152:153], 1, v[14:15]
	s_mov_b64 s[8:9], 0
	global_store_dwordx4 v[14:15], v[10:13], off

.LBB0_1243:
	v_lshl_add_u32 v142, s8, 8, v146
	v_and_b32_e32 v140, -16, v142
	v_lshlrev_b32_e32 v140, 6, v140
	v_lshl_add_u32 v140, v186, 4, v140
	v_add_u32_e32 v230, 0x2000, v140
	global_load_dwordx4 v[198:201], v140, s[2:3]
	global_load_dwordx4 v[202:205], v140, s[2:3] offset:1024
	global_load_dwordx4 v[206:209], v140, s[2:3] offset:2048
	global_load_dwordx4 v[210:213], v140, s[2:3] offset:3072
	global_load_dwordx4 v[214:217], v230, s[2:3]
	global_load_dwordx4 v[218:221], v230, s[2:3] offset:1024
	global_load_dwordx4 v[222:225], v230, s[2:3] offset:2048
	global_load_dwordx4 v[226:229], v230, s[2:3] offset:3072
	v_and_b32_e32 v231, 15, v186
	v_lshlrev_b32_e32 v231, 4, v231
	s_waitcnt vmcnt(0)
	v_add_f32_e32 v198, v198, v199
	v_add_f32_e32 v200, v200, v201
	v_add_f32_e32 v202, v202, v203
	v_add_f32_e32 v204, v204, v205
	v_add_f32_e32 v206, v206, v207
	v_add_f32_e32 v208, v208, v209
	v_add_f32_e32 v210, v210, v211
	v_add_f32_e32 v212, v212, v213
	v_add_f32_e32 v214, v214, v215
	v_add_f32_e32 v216, v216, v217
	v_add_f32_e32 v218, v218, v219
	v_add_f32_e32 v220, v220, v221
	v_add_f32_e32 v222, v222, v223
	v_add_f32_e32 v224, v224, v225
	v_add_f32_e32 v226, v226, v227
	v_add_f32_e32 v228, v228, v229
	v_add_f32_e32 v198, v198, v200
	v_add_f32_e32 v202, v202, v204
	v_add_f32_e32 v206, v206, v208
	v_add_f32_e32 v210, v210, v212
	v_add_f32_e32 v214, v214, v216
	v_add_f32_e32 v218, v218, v220
	v_add_f32_e32 v222, v222, v224
	v_add_f32_e32 v226, v226, v228
	v_add_f32_dpp v198, v198, v198 quad_perm:[1,0,3,2] row_mask:0xf bank_mask:0xf
	v_add_f32_dpp v202, v202, v202 quad_perm:[1,0,3,2] row_mask:0xf bank_mask:0xf
	v_add_f32_dpp v206, v206, v206 quad_perm:[1,0,3,2] row_mask:0xf bank_mask:0xf
	v_add_f32_dpp v210, v210, v210 quad_perm:[1,0,3,2] row_mask:0xf bank_mask:0xf
	v_add_f32_dpp v214, v214, v214 quad_perm:[1,0,3,2] row_mask:0xf bank_mask:0xf
	v_add_f32_dpp v218, v218, v218 quad_perm:[1,0,3,2] row_mask:0xf bank_mask:0xf
	v_add_f32_dpp v222, v222, v222 quad_perm:[1,0,3,2] row_mask:0xf bank_mask:0xf
	v_add_f32_dpp v226, v226, v226 quad_perm:[1,0,3,2] row_mask:0xf bank_mask:0xf
	v_add_f32_dpp v198, v198, v198 quad_perm:[2,3,0,1] row_mask:0xf bank_mask:0xf
	v_add_f32_dpp v202, v202, v202 quad_perm:[2,3,0,1] row_mask:0xf bank_mask:0xf
	v_add_f32_dpp v206, v206, v206 quad_perm:[2,3,0,1] row_mask:0xf bank_mask:0xf
	v_add_f32_dpp v210, v210, v210 quad_perm:[2,3,0,1] row_mask:0xf bank_mask:0xf
	v_add_f32_dpp v214, v214, v214 quad_perm:[2,3,0,1] row_mask:0xf bank_mask:0xf
	v_add_f32_dpp v218, v218, v218 quad_perm:[2,3,0,1] row_mask:0xf bank_mask:0xf
	v_add_f32_dpp v222, v222, v222 quad_perm:[2,3,0,1] row_mask:0xf bank_mask:0xf
	v_add_f32_dpp v226, v226, v226 quad_perm:[2,3,0,1] row_mask:0xf bank_mask:0xf
	v_fmamk_f32 v198, v198, 0x3a800000, v182
	v_fmamk_f32 v202, v202, 0x3a800000, v182
	v_fmamk_f32 v206, v206, 0x3a800000, v182
	v_fmamk_f32 v210, v210, 0x3a800000, v182
	v_fmamk_f32 v214, v214, 0x3a800000, v182
	v_fmamk_f32 v218, v218, 0x3a800000, v182
	v_fmamk_f32 v222, v222, 0x3a800000, v182
	v_fmamk_f32 v226, v226, 0x3a800000, v182
	v_mul_f32_e32 v199, 0x4b800000, v198
	v_mul_f32_e32 v203, 0x4b800000, v202
	v_mul_f32_e32 v207, 0x4b800000, v206
	v_mul_f32_e32 v211, 0x4b800000, v210
	v_mul_f32_e32 v215, 0x4b800000, v214
	v_mul_f32_e32 v219, 0x4b800000, v218
	v_mul_f32_e32 v223, 0x4b800000, v222
	v_mul_f32_e32 v227, 0x4b800000, v226
	v_cmp_gt_f32_e32 vcc, 0x800000, v198
	s_nop 1
	v_cndmask_b32_e32 v200, v198, v199, vcc
	v_rsq_f32_e32 v200, v200
	s_nop 0
	v_mul_f32_e32 v201, 0x45800000, v200
	v_cndmask_b32_e32 v200, v200, v201, vcc
	v_cmp_gt_f32_e32 vcc, 0x800000, v202
	s_nop 1
	v_cndmask_b32_e32 v204, v202, v203, vcc
	v_rsq_f32_e32 v204, v204
	s_nop 0
	v_mul_f32_e32 v205, 0x45800000, v204
	v_cndmask_b32_e32 v204, v204, v205, vcc
	v_cmp_gt_f32_e32 vcc, 0x800000, v206
	s_nop 1
	v_cndmask_b32_e32 v208, v206, v207, vcc
	v_rsq_f32_e32 v208, v208
	s_nop 0
	v_mul_f32_e32 v209, 0x45800000, v208
	v_cndmask_b32_e32 v208, v208, v209, vcc
	v_cmp_gt_f32_e32 vcc, 0x800000, v210
	s_nop 1
	v_cndmask_b32_e32 v212, v210, v211, vcc
	v_rsq_f32_e32 v212, v212
	s_nop 0
	v_mul_f32_e32 v213, 0x45800000, v212
	v_cndmask_b32_e32 v212, v212, v213, vcc
	v_cmp_gt_f32_e32 vcc, 0x800000, v214
	s_nop 1
	v_cndmask_b32_e32 v216, v214, v215, vcc
	v_rsq_f32_e32 v216, v216
	s_nop 0
	v_mul_f32_e32 v217, 0x45800000, v216
	v_cndmask_b32_e32 v216, v216, v217, vcc
	v_cmp_gt_f32_e32 vcc, 0x800000, v218
	s_nop 1
	v_cndmask_b32_e32 v220, v218, v219, vcc
	v_rsq_f32_e32 v220, v220
	s_nop 0
	v_mul_f32_e32 v221, 0x45800000, v220
	v_cndmask_b32_e32 v220, v220, v221, vcc
	v_cmp_gt_f32_e32 vcc, 0x800000, v222
	s_nop 1
	v_cndmask_b32_e32 v224, v222, v223, vcc
	v_rsq_f32_e32 v224, v224
	s_nop 0
	v_mul_f32_e32 v225, 0x45800000, v224
	v_cndmask_b32_e32 v224, v224, v225, vcc
	v_cmp_gt_f32_e32 vcc, 0x800000, v226
	s_nop 1
	v_cndmask_b32_e32 v228, v226, v227, vcc
	v_rsq_f32_e32 v228, v228
	s_nop 0
	v_mul_f32_e32 v229, 0x45800000, v228
	v_cndmask_b32_e32 v228, v228, v229, vcc
	s_nop 1
	ds_bpermute_b32 v242, v231, v200
	ds_bpermute_b32 v243, v231, v204
	ds_bpermute_b32 v244, v231, v208
	ds_bpermute_b32 v245, v231, v212
	ds_bpermute_b32 v246, v231, v216
	ds_bpermute_b32 v247, v231, v220
	ds_bpermute_b32 v248, v231, v224
	ds_bpermute_b32 v249, v231, v228
	s_waitcnt lgkmcnt(0)
	v_ashrrev_i32_e32 v143, 31, v142
	v_lshlrev_b64 v[140:141], 6, v[142:143]
	v_lshl_add_u64 v[140:141], s[2:3], 0, v[140:141]
	v_lshl_or_b32 v140, s0, 8, v148
	s_movk_i32 s0, 0x1000
	v_mov_b32_e32 v144, v242
	v_mov_b32_e32 v145, v144
	v_cmp_gt_i32_e32 vcc, s0, v140
	s_and_saveexec_b64 s[0:1], vcc
	s_cbranch_execz .LBB0_1245
	v_mov_b32_e32 v150, v144
	v_mov_b32_e32 v151, v144
	v_pk_mul_f32 v[126:127], v[126:127], v[144:145]
	v_pk_mul_f32 v[122:123], v[122:123], v[144:145]
	v_pk_mul_f32 v[128:129], v[128:129], v[150:151]
	v_max_f32_e32 v126, 0, v126
	v_max_f32_e32 v122, 0, v122
	v_max_f32_e32 v127, 0, v127
	v_max_f32_e32 v123, 0, v123
	v_pk_mul_f32 v[124:125], v[124:125], v[150:151]
	v_pk_mul_f32 v[126:127], v[126:127], v[126:127]
	v_pk_mul_f32 v[150:151], v[122:123], v[122:123]
	v_max_f32_e32 v122, 0, v128
	v_max_f32_e32 v123, 0, v129
	v_max_f32_e32 v124, 0, v124
	v_max_f32_e32 v125, 0, v125
	v_pk_mul_f32 v[128:129], v[122:123], v[122:123]
	v_cvt_pk_bf16_f32 v122, v126, v127
	v_lshlrev_b64 v[126:127], 13, v[142:143]
	v_pk_mul_f32 v[152:153], v[124:125], v[124:125]
	v_lshl_add_u64 v[126:127], s[10:11], 0, v[126:127]
	v_ashrrev_i32_e32 v141, 31, v140
	v_cvt_pk_bf16_f32 v123, v128, v129
	v_cvt_pk_bf16_f32 v124, v150, v151
	v_cvt_pk_bf16_f32 v125, v152, v153
	v_lshl_add_u64 v[126:127], v[140:141], 1, v[126:127]
	global_store_dwordx4 v[126:127], v[122:125], off

.LBB0_1247:
	s_or_b64 exec, exec, s[0:1]
	s_nop 0
	v_or_b32_e32 v114, 16, v142
	v_ashrrev_i32_e32 v115, 31, v114
	v_lshlrev_b64 v[116:117], 6, v[114:115]
	v_lshl_add_u64 v[128:129], s[2:3], 0, v[116:117]
	v_mov_b32_e32 v116, v243
	v_mov_b32_e32 v117, v116
	s_and_saveexec_b64 s[0:1], vcc
	s_cbranch_execz .LBB0_1249
	v_mov_b32_e32 v118, v116
	v_mov_b32_e32 v119, v116
	v_pk_mul_f32 v[110:111], v[110:111], v[116:117]
	v_pk_mul_f32 v[106:107], v[106:107], v[116:117]
	v_pk_mul_f32 v[112:113], v[112:113], v[118:119]
	v_max_f32_e32 v110, 0, v110
	v_max_f32_e32 v106, 0, v106
	v_max_f32_e32 v111, 0, v111
	v_max_f32_e32 v107, 0, v107
	v_pk_mul_f32 v[108:109], v[108:109], v[118:119]
	v_pk_mul_f32 v[110:111], v[110:111], v[110:111]
	v_pk_mul_f32 v[118:119], v[106:107], v[106:107]
	v_max_f32_e32 v106, 0, v112
	v_max_f32_e32 v107, 0, v113
	v_max_f32_e32 v108, 0, v108
	v_max_f32_e32 v109, 0, v109
	v_pk_mul_f32 v[112:113], v[106:107], v[106:107]
	v_cvt_pk_bf16_f32 v106, v110, v111
	v_lshlrev_b64 v[110:111], 13, v[114:115]
	v_pk_mul_f32 v[120:121], v[108:109], v[108:109]
	v_lshl_add_u64 v[110:111], s[10:11], 0, v[110:111]
	v_ashrrev_i32_e32 v141, 31, v140
	v_cvt_pk_bf16_f32 v107, v112, v113
	v_cvt_pk_bf16_f32 v108, v118, v119
	v_cvt_pk_bf16_f32 v109, v120, v121
	v_lshl_add_u64 v[110:111], v[140:141], 1, v[110:111]
	global_store_dwordx4 v[110:111], v[106:109], off

.LBB0_1251:
	s_or_b64 exec, exec, s[0:1]
	s_nop 0
	v_or_b32_e32 v98, 32, v142
	v_ashrrev_i32_e32 v99, 31, v98
	v_lshlrev_b64 v[100:101], 6, v[98:99]
	v_lshl_add_u64 v[112:113], s[2:3], 0, v[100:101]
	v_mov_b32_e32 v100, v244
	v_mov_b32_e32 v101, v100
	s_and_saveexec_b64 s[0:1], vcc
	s_cbranch_execz .LBB0_1253
	v_mov_b32_e32 v102, v100
	v_mov_b32_e32 v103, v100
	v_pk_mul_f32 v[94:95], v[94:95], v[100:101]
	v_pk_mul_f32 v[90:91], v[90:91], v[100:101]
	v_pk_mul_f32 v[96:97], v[96:97], v[102:103]
	v_max_f32_e32 v94, 0, v94
	v_max_f32_e32 v90, 0, v90
	v_max_f32_e32 v95, 0, v95
	v_max_f32_e32 v91, 0, v91
	v_pk_mul_f32 v[92:93], v[92:93], v[102:103]
	v_pk_mul_f32 v[94:95], v[94:95], v[94:95]
	v_pk_mul_f32 v[102:103], v[90:91], v[90:91]
	v_max_f32_e32 v90, 0, v96
	v_max_f32_e32 v91, 0, v97
	v_max_f32_e32 v92, 0, v92
	v_max_f32_e32 v93, 0, v93
	v_pk_mul_f32 v[96:97], v[90:91], v[90:91]
	v_cvt_pk_bf16_f32 v90, v94, v95
	v_lshlrev_b64 v[94:95], 13, v[98:99]
	v_pk_mul_f32 v[104:105], v[92:93], v[92:93]
	v_lshl_add_u64 v[94:95], s[10:11], 0, v[94:95]
	v_ashrrev_i32_e32 v141, 31, v140
	v_cvt_pk_bf16_f32 v91, v96, v97
	v_cvt_pk_bf16_f32 v92, v102, v103
	v_cvt_pk_bf16_f32 v93, v104, v105
	v_lshl_add_u64 v[94:95], v[140:141], 1, v[94:95]
	global_store_dwordx4 v[94:95], v[90:93], off

.LBB0_1255:
	s_or_b64 exec, exec, s[0:1]
	s_nop 0
	v_or_b32_e32 v82, 48, v142
	v_ashrrev_i32_e32 v83, 31, v82
	v_lshlrev_b64 v[84:85], 6, v[82:83]
	v_lshl_add_u64 v[96:97], s[2:3], 0, v[84:85]
	v_mov_b32_e32 v84, v245
	v_mov_b32_e32 v85, v84
	s_and_saveexec_b64 s[0:1], vcc
	s_cbranch_execz .LBB0_1257
	v_mov_b32_e32 v86, v84
	v_mov_b32_e32 v87, v84
	v_pk_mul_f32 v[78:79], v[78:79], v[84:85]
	v_pk_mul_f32 v[74:75], v[74:75], v[84:85]
	v_pk_mul_f32 v[80:81], v[80:81], v[86:87]
	v_max_f32_e32 v78, 0, v78
	v_max_f32_e32 v74, 0, v74
	v_max_f32_e32 v79, 0, v79
	v_max_f32_e32 v75, 0, v75
	v_pk_mul_f32 v[76:77], v[76:77], v[86:87]
	v_pk_mul_f32 v[78:79], v[78:79], v[78:79]
	v_pk_mul_f32 v[86:87], v[74:75], v[74:75]
	v_max_f32_e32 v74, 0, v80
	v_max_f32_e32 v75, 0, v81
	v_max_f32_e32 v76, 0, v76
	v_max_f32_e32 v77, 0, v77
	v_pk_mul_f32 v[80:81], v[74:75], v[74:75]
	v_cvt_pk_bf16_f32 v74, v78, v79
	v_lshlrev_b64 v[78:79], 13, v[82:83]
	v_pk_mul_f32 v[88:89], v[76:77], v[76:77]
	v_lshl_add_u64 v[78:79], s[10:11], 0, v[78:79]
	v_ashrrev_i32_e32 v141, 31, v140
	v_cvt_pk_bf16_f32 v75, v80, v81
	v_cvt_pk_bf16_f32 v76, v86, v87
	v_cvt_pk_bf16_f32 v77, v88, v89
	v_lshl_add_u64 v[78:79], v[140:141], 1, v[78:79]
	global_store_dwordx4 v[78:79], v[74:77], off

.LBB0_1259:
	s_or_b64 exec, exec, s[0:1]
	s_nop 0
	v_add_u32_e32 v66, 0x80, v142
	v_ashrrev_i32_e32 v67, 31, v66
	v_lshlrev_b64 v[68:69], 6, v[66:67]
	v_lshl_add_u64 v[80:81], s[2:3], 0, v[68:69]
	v_mov_b32_e32 v68, v246
	v_mov_b32_e32 v69, v68
	s_and_saveexec_b64 s[0:1], vcc
	s_cbranch_execz .LBB0_1261
	v_mov_b32_e32 v70, v68
	v_mov_b32_e32 v71, v68
	v_pk_mul_f32 v[62:63], v[62:63], v[68:69]
	v_pk_mul_f32 v[58:59], v[58:59], v[68:69]
	v_pk_mul_f32 v[64:65], v[64:65], v[70:71]
	v_max_f32_e32 v62, 0, v62
	v_max_f32_e32 v58, 0, v58
	v_max_f32_e32 v63, 0, v63
	v_max_f32_e32 v59, 0, v59
	v_pk_mul_f32 v[60:61], v[60:61], v[70:71]
	v_pk_mul_f32 v[62:63], v[62:63], v[62:63]
	v_pk_mul_f32 v[70:71], v[58:59], v[58:59]
	v_max_f32_e32 v58, 0, v64
	v_max_f32_e32 v59, 0, v65
	v_max_f32_e32 v60, 0, v60
	v_max_f32_e32 v61, 0, v61
	v_pk_mul_f32 v[64:65], v[58:59], v[58:59]
	v_cvt_pk_bf16_f32 v58, v62, v63
	v_lshlrev_b64 v[62:63], 13, v[66:67]
	v_pk_mul_f32 v[72:73], v[60:61], v[60:61]
	v_lshl_add_u64 v[62:63], s[10:11], 0, v[62:63]
	v_ashrrev_i32_e32 v141, 31, v140
	v_cvt_pk_bf16_f32 v59, v64, v65
	v_cvt_pk_bf16_f32 v60, v70, v71
	v_cvt_pk_bf16_f32 v61, v72, v73
	v_lshl_add_u64 v[62:63], v[140:141], 1, v[62:63]
	global_store_dwordx4 v[62:63], v[58:61], off

.LBB0_1263:
	s_or_b64 exec, exec, s[0:1]
	s_nop 0
	v_add_u32_e32 v50, 0x90, v142
	v_ashrrev_i32_e32 v51, 31, v50
	v_lshlrev_b64 v[52:53], 6, v[50:51]
	v_lshl_add_u64 v[64:65], s[2:3], 0, v[52:53]
	v_mov_b32_e32 v52, v247
	v_mov_b32_e32 v53, v52
	s_and_saveexec_b64 s[0:1], vcc
	s_cbranch_execz .LBB0_1265
	v_mov_b32_e32 v54, v52
	v_mov_b32_e32 v55, v52
	v_pk_mul_f32 v[46:47], v[46:47], v[52:53]
	v_pk_mul_f32 v[42:43], v[42:43], v[52:53]
	v_pk_mul_f32 v[48:49], v[48:49], v[54:55]
	v_max_f32_e32 v46, 0, v46
	v_max_f32_e32 v42, 0, v42
	v_max_f32_e32 v47, 0, v47
	v_max_f32_e32 v43, 0, v43
	v_pk_mul_f32 v[44:45], v[44:45], v[54:55]
	v_pk_mul_f32 v[46:47], v[46:47], v[46:47]
	v_pk_mul_f32 v[54:55], v[42:43], v[42:43]
	v_max_f32_e32 v42, 0, v48
	v_max_f32_e32 v43, 0, v49
	v_max_f32_e32 v44, 0, v44
	v_max_f32_e32 v45, 0, v45
	v_pk_mul_f32 v[48:49], v[42:43], v[42:43]
	v_cvt_pk_bf16_f32 v42, v46, v47
	v_lshlrev_b64 v[46:47], 13, v[50:51]
	v_pk_mul_f32 v[56:57], v[44:45], v[44:45]
	v_lshl_add_u64 v[46:47], s[10:11], 0, v[46:47]
	v_ashrrev_i32_e32 v141, 31, v140
	v_cvt_pk_bf16_f32 v43, v48, v49
	v_cvt_pk_bf16_f32 v44, v54, v55
	v_cvt_pk_bf16_f32 v45, v56, v57
	v_lshl_add_u64 v[46:47], v[140:141], 1, v[46:47]
	global_store_dwordx4 v[46:47], v[42:45], off

.LBB0_1267:
	s_or_b64 exec, exec, s[0:1]
	s_nop 0
	v_add_u32_e32 v34, 0xa0, v142
	v_ashrrev_i32_e32 v35, 31, v34
	v_lshlrev_b64 v[36:37], 6, v[34:35]
	v_lshl_add_u64 v[48:49], s[2:3], 0, v[36:37]
	v_mov_b32_e32 v36, v248
	v_mov_b32_e32 v37, v36
	s_and_saveexec_b64 s[0:1], vcc
	s_cbranch_execz .LBB0_1269
	v_mov_b32_e32 v38, v36
	v_mov_b32_e32 v39, v36
	v_pk_mul_f32 v[30:31], v[30:31], v[36:37]
	v_pk_mul_f32 v[26:27], v[26:27], v[36:37]
	v_pk_mul_f32 v[32:33], v[32:33], v[38:39]
	v_max_f32_e32 v30, 0, v30
	v_max_f32_e32 v26, 0, v26
	v_max_f32_e32 v31, 0, v31
	v_max_f32_e32 v27, 0, v27
	v_pk_mul_f32 v[28:29], v[28:29], v[38:39]
	v_pk_mul_f32 v[30:31], v[30:31], v[30:31]
	v_pk_mul_f32 v[38:39], v[26:27], v[26:27]
	v_max_f32_e32 v26, 0, v32
	v_max_f32_e32 v27, 0, v33
	v_max_f32_e32 v28, 0, v28
	v_max_f32_e32 v29, 0, v29
	v_pk_mul_f32 v[32:33], v[26:27], v[26:27]
	v_cvt_pk_bf16_f32 v26, v30, v31
	v_lshlrev_b64 v[30:31], 13, v[34:35]
	v_pk_mul_f32 v[40:41], v[28:29], v[28:29]
	v_lshl_add_u64 v[30:31], s[10:11], 0, v[30:31]
	v_ashrrev_i32_e32 v141, 31, v140
	v_cvt_pk_bf16_f32 v27, v32, v33
	v_cvt_pk_bf16_f32 v28, v38, v39
	v_cvt_pk_bf16_f32 v29, v40, v41
	v_lshl_add_u64 v[30:31], v[140:141], 1, v[30:31]
	global_store_dwordx4 v[30:31], v[26:29], off

.LBB0_1271:
	s_or_b64 exec, exec, s[0:1]
	s_nop 0
	v_add_u32_e32 v18, 0xb0, v142
	v_ashrrev_i32_e32 v19, 31, v18
	v_lshlrev_b64 v[20:21], 6, v[18:19]
	v_lshl_add_u64 v[32:33], s[2:3], 0, v[20:21]
	v_mov_b32_e32 v20, v249
	v_mov_b32_e32 v21, v20
	s_and_saveexec_b64 s[0:1], vcc
	s_cbranch_execz .LBB0_1273
	v_mov_b32_e32 v22, v20
	v_mov_b32_e32 v23, v20
	v_pk_mul_f32 v[14:15], v[14:15], v[20:21]
	v_pk_mul_f32 v[10:11], v[10:11], v[20:21]
	v_pk_mul_f32 v[16:17], v[16:17], v[22:23]
	v_max_f32_e32 v14, 0, v14
	v_max_f32_e32 v10, 0, v10
	v_max_f32_e32 v15, 0, v15
	v_max_f32_e32 v11, 0, v11
	v_pk_mul_f32 v[12:13], v[12:13], v[22:23]
	v_pk_mul_f32 v[14:15], v[14:15], v[14:15]
	v_pk_mul_f32 v[22:23], v[10:11], v[10:11]
	v_max_f32_e32 v10, 0, v16
	v_max_f32_e32 v11, 0, v17
	v_max_f32_e32 v12, 0, v12
	v_max_f32_e32 v13, 0, v13
	v_pk_mul_f32 v[16:17], v[10:11], v[10:11]
	v_cvt_pk_bf16_f32 v10, v14, v15
	v_lshlrev_b64 v[14:15], 13, v[18:19]
	v_pk_mul_f32 v[24:25], v[12:13], v[12:13]
	v_lshl_add_u64 v[14:15], s[10:11], 0, v[14:15]
	v_ashrrev_i32_e32 v141, 31, v140
	v_cvt_pk_bf16_f32 v11, v16, v17
	v_cvt_pk_bf16_f32 v12, v22, v23
	v_cvt_pk_bf16_f32 v13, v24, v25
	v_lshl_add_u64 v[14:15], v[140:141], 1, v[14:15]
	global_store_dwordx4 v[14:15], v[10:13], off
